# FoX Q/K for layer 1 stored head-major (Qh|Kh [b][h][w][64]) by the QK GEMM epilogue, FoX loaders follow; on top of the pipelined FoX loop
# baseline (speedup 1.0000x reference)
.LBB0_163:
	s_lshl_b32 s4, s71, 2
	s_add_i32 s40, s4, 0
	s_cmp_gt_i32 s71, 0
	s_cselect_b64 s[28:29], -1, 0
	s_lshl_b32 s6, s71, 5
	s_cmp_lt_i32 s71, 4
	v_lshrrev_b32_e32 v2, 5, v243
	s_cselect_b64 s[4:5], -1, 0
	s_cmp_gt_i32 s71, 3
	v_lshlrev_b32_e32 v166, 3, v2
	v_lshlrev_b32_e32 v2, 4, v2
	v_mov_b32_e32 v3, v0
	s_cselect_b64 s[30:31], -1, 0
	s_lshl_b32 s34, s71, 4
	v_lshl_add_u64 v[168:169], s[96:97], 0, v[2:3]
	v_lshl_add_u64 v[2:3], s[82:83], 0, v[2:3]
	s_add_i32 s7, s34, 0x7fffffc0
	s_and_b32 s78, s6, 32
	v_and_b32_e32 v4, 31, v242
	s_and_b32 s7, s7, 0x7fffffe0
	v_lshl_add_u64 v[170:171], v[2:3], 0, s[78:79]
	v_lshrrev_b32_e32 v2, 1, v242
	v_lshlrev_b32_e32 v3, 1, v243
	v_or_b32_e32 v186, s6, v4
	v_or_b32_e32 v187, s7, v4
	v_and_b32_e32 v2, 4, v2
	v_and_b32_e32 v3, 8, v3
	v_and_b32_e32 v4, 19, v242
	v_and_b32_e32 v1, 64, v238
	v_or3_b32 v188, v2, v4, v3
	v_add_u32_e32 v2, -1, v238
	v_cmp_lt_i32_e32 vcc, v2, v1
	v_mov_b32_e32 v167, v0
	v_lshl_add_u64 v[172:173], s[18:19], 0, v[166:167]
	v_cndmask_b32_e32 v2, v2, v238, vcc
	v_lshlrev_b32_e32 v167, 2, v2
	v_add_u32_e32 v2, -2, v238
	v_cmp_lt_i32_e32 vcc, v2, v1
	s_ashr_i32 s35, s34, 31
	s_and_b64 s[36:37], s[4:5], exec
	v_cndmask_b32_e32 v2, v2, v238, vcc
	v_lshlrev_b32_e32 v190, 2, v2
	v_add_u32_e32 v2, -4, v238
	v_cmp_lt_i32_e32 vcc, v2, v1
	s_cselect_b32 s36, 0x800, 32
	v_readlane_b32 s37, v255, 5
	v_cndmask_b32_e32 v2, v2, v238, vcc
	v_lshlrev_b32_e32 v191, 2, v2
	v_add_u32_e32 v2, -8, v238
	v_cmp_lt_i32_e32 vcc, v2, v1
	v_lshlrev_b32_e32 v184, 3, v242
	v_cmp_eq_u32_e64 s[2:3], 63, v243
	v_cndmask_b32_e32 v2, v2, v238, vcc
	v_lshlrev_b32_e32 v192, 2, v2
	v_add_u32_e32 v2, -16, v238
	v_cmp_lt_i32_e32 vcc, v2, v1
	v_lshl_add_u32 v185, v242, 5, 0
	v_lshl_add_u32 v189, v243, 4, 0
	v_cndmask_b32_e32 v2, v2, v238, vcc
	v_lshlrev_b32_e32 v193, 2, v2
	v_subrev_u32_e32 v2, 32, v238
	v_cmp_lt_i32_e32 vcc, v2, v1
	v_add_u32_e32 v1, 64, v1
	v_cmp_eq_u32_e64 s[6:7], 0, v243
	v_cndmask_b32_e32 v2, v2, v238, vcc
	v_lshlrev_b32_e32 v202, 2, v2
	v_xor_b32_e32 v2, 32, v238
	v_cmp_lt_i32_e32 vcc, v2, v1
	v_cmp_gt_u32_e64 s[8:9], 2, v243
	v_cmp_gt_u32_e64 s[10:11], 4, v243
	v_cndmask_b32_e32 v1, v238, v2, vcc
	v_lshlrev_b32_e32 v203, 2, v1
	v_and_b32_e32 v1, 32, v243
	v_cmp_gt_u32_e64 s[12:13], 8, v243
	v_cmp_gt_u32_e64 s[14:15], 16, v243
	v_cmp_gt_u32_e64 s[16:17], 32, v243
	s_cselect_b32 s41, 6, 0
	v_add_u32_e32 v204, s37, v1
	v_lshlrev_b32_e32 v174, 1, v166
	s_lshl_b32 s36, s36, 1
	s_branch .LBB0_165

.LBB0_170:
	v_pk_add_f32 v[6:7], v[10:11], v[6:7] op_sel_hi:[0,1]
	v_pk_add_f32 v[8:9], v[10:11], v[8:9] op_sel_hi:[0,1]
	v_xor_b32_e32 v7, 0x80000000, v7
	v_xor_b32_e32 v6, 0x80000000, v6
	v_xor_b32_e32 v9, 0x80000000, v9
	v_xor_b32_e32 v8, 0x80000000, v8
	v_pk_add_f32 v[4:5], v[10:11], v[4:5] op_sel_hi:[0,1]
	v_pk_add_f32 v[2:3], v[10:11], v[2:3] op_sel_hi:[0,1]
	ds_write_b128 v185, v[6:9]
	v_xor_b32_e32 v5, 0x80000000, v5
	v_xor_b32_e32 v4, 0x80000000, v4
	v_xor_b32_e32 v7, 0x80000000, v3
	v_xor_b32_e32 v6, 0x80000000, v2
	ds_write_b128 v185, v[4:7] offset:16
	v_or_b32_e32 v4, s37, v188
	v_ashrrev_i32_e32 v5, 31, v4
	s_lshl_b32 s38, s44, 6
	s_lshl_b32 s39, s43, 10
	s_mul_i32 s98, s43, 15
	s_add_i32 s98, s98, s44
	s_lshl_b32 s98, s98, 19
	s_mov_b32 s99, 0
	s_or_b32 s100, s98, 0x4000000
	s_mov_b32 s101, 0
	v_lshlrev_b64 v[4:5], 7, v[4:5]
	s_lshl_b32 s78, s44, 7
	s_or_b32 s38, s38, s39
	v_lshl_add_u64 v[4:5], s[96:97], 0, v[4:5]
	v_add_u32_e32 v2, s38, v187
	v_lshl_add_u64 v[4:5], v[4:5], 0, s[100:101]
	v_mov_b32_e32 v175, v0
	v_ashrrev_i32_e32 v3, 31, v2
	v_lshl_add_u64 v[4:5], v[4:5], 0, v[174:175]
	v_lshlrev_b64 v[2:3], 13, v[2:3]
	v_lshl_add_u64 v[4:5], s[34:35], 1, v[4:5]
	s_mov_b64 s[38:39], 0x800
	v_lshl_add_u64 v[2:3], v[170:171], 0, v[2:3]
	s_and_b32 s42, s33, 1
	v_add_u32_e32 v205, s37, v186
	v_lshl_add_u64 v[176:177], v[168:169], 0, s[98:99]
	v_lshl_add_u64 v[178:179], v[172:173], 0, s[78:79]
	v_cndmask_b32_e64 v181, v3, v5, s[4:5]
	v_cndmask_b32_e64 v180, v2, v4, s[4:5]
	s_mov_b32 s43, 0
	s_waitcnt lgkmcnt(0)
	s_barrier
	s_branch .LBB0_172

.LBB0_172:
	s_and_b32 s38, s43, 6
	s_xor_b32 s38, s38, 15
	s_and_b32 s37, s43, 1
	s_sub_i32 s38, s38, s42
	s_or_b32 s39, s43, s42
	s_cmp_eq_u32 s37, 0
	s_cselect_b32 s38, s39, s38
	s_lshl_b32 s44, s38, 8
	v_add_u32_e32 v182, s44, v205
	v_ashrrev_i32_e32 v183, 31, v182
	v_lshlrev_b64 v[2:3], 7, v[182:183]
	v_lshl_add_u64 v[2:3], v[176:177], 0, v[2:3]
	global_load_dwordx4 v[66:69], v[2:3], off
	global_load_dwordx4 v[70:73], v[2:3], off offset:32
	global_load_dwordx4 v[74:77], v[2:3], off offset:64
	global_load_dwordx4 v[78:81], v[2:3], off offset:96
	s_andn2_b64 vcc, exec, s[30:31]
	s_cbranch_vccnz .LBB0_174
	s_setprio 1

.LBB0_226:
	s_lshr_b32 s98, s33, 2
	s_lshl_b32 s98, s98, 26
	s_lshr_b32 s99, s43, 4
	s_mul_i32 s99, s99, 15
	s_and_b32 s100, s33, 3
	s_lshl_b32 s100, s100, 2
	s_add_i32 s99, s99, s100
	s_and_b32 s100, s71, 3
	s_lshr_b32 s100, s100, 1
	s_add_i32 s99, s99, s100
	s_lshl_b32 s99, s99, 19
	s_add_u32 s98, s98, s99
	s_add_u32 s98, s96, s98
	s_addc_u32 s99, s97, 0
	s_mov_b32 s100, 0x100000
	s_mov_b32 s101, 0
	v_and_b32_e32 v130, 63, v147
	v_cndmask_b32_e64 v132, 1.0, v240, s[4:5]
	s_andn2_b64 vcc, exec, s[26:27]
	v_ashrrev_i32_e32 v131, 31, v130
	s_cbranch_vccnz .LBB0_228
	v_mul_f32_e32 v134, v132, v224
	v_lshlrev_b64 v[136:137], 7, v[186:187]
	v_pk_mul_f32 v[126:127], v[126:127], v[134:135] op_sel_hi:[1,0]
	v_pk_mul_f32 v[128:129], v[128:129], v[134:135] op_sel_hi:[1,0]
	v_pk_mul_f32 v[186:187], v[124:125], v[134:135] op_sel_hi:[1,0]
	v_pk_mul_f32 v[124:125], v[122:123], v[134:135] op_sel_hi:[1,0]
	v_cvt_pk_bf16_f32 v122, v126, v127
	v_lshl_add_u64 v[126:127], s[98:99], 0, v[136:137]
	v_cvt_pk_bf16_f32 v123, v128, v129
	v_cvt_pk_bf16_f32 v124, v124, v125
	v_cvt_pk_bf16_f32 v125, v186, v187
	v_lshl_add_u64 v[126:127], v[130:131], 1, v[126:127]
	global_store_dwordx4 v[126:127], v[122:125], off
	v_pk_mul_f32 v[120:121], v[120:121], v[134:135] op_sel_hi:[1,0]
	v_pk_mul_f32 v[118:119], v[118:119], v[134:135] op_sel_hi:[1,0]
	v_pk_mul_f32 v[122:123], v[116:117], v[134:135] op_sel_hi:[1,0]
	v_pk_mul_f32 v[116:117], v[114:115], v[134:135] op_sel_hi:[1,0]
	v_cvt_pk_bf16_f32 v114, v118, v119
	v_cvt_pk_bf16_f32 v115, v120, v121
	v_cvt_pk_bf16_f32 v116, v116, v117
	v_cvt_pk_bf16_f32 v117, v122, v123
	v_lshl_add_u64 v[126:127], v[126:127], 0, s[100:101]
	global_store_dwordx4 v[126:127], v[114:117], off

.LBB0_232:
	s_andn2_b64 vcc, exec, s[24:25]
	s_cbranch_vccnz .LBB0_234
	v_mul_f32_e32 v114, v132, v122
	v_lshlrev_b64 v[116:117], 7, v[182:183]
	v_pk_mul_f32 v[110:111], v[110:111], v[114:115] op_sel_hi:[1,0]
	v_pk_mul_f32 v[112:113], v[112:113], v[114:115] op_sel_hi:[1,0]
	v_pk_mul_f32 v[118:119], v[108:109], v[114:115] op_sel_hi:[1,0]
	v_pk_mul_f32 v[108:109], v[106:107], v[114:115] op_sel_hi:[1,0]
	v_cvt_pk_bf16_f32 v106, v110, v111
	v_lshl_add_u64 v[110:111], s[98:99], 0, v[116:117]
	v_cvt_pk_bf16_f32 v107, v112, v113
	v_cvt_pk_bf16_f32 v108, v108, v109
	v_cvt_pk_bf16_f32 v109, v118, v119
	v_lshl_add_u64 v[110:111], v[130:131], 1, v[110:111]
	global_store_dwordx4 v[110:111], v[106:109], off
	v_pk_mul_f32 v[104:105], v[104:105], v[114:115] op_sel_hi:[1,0]
	v_pk_mul_f32 v[102:103], v[102:103], v[114:115] op_sel_hi:[1,0]
	v_pk_mul_f32 v[106:107], v[100:101], v[114:115] op_sel_hi:[1,0]
	v_pk_mul_f32 v[100:101], v[98:99], v[114:115] op_sel_hi:[1,0]
	v_cvt_pk_bf16_f32 v98, v102, v103
	v_cvt_pk_bf16_f32 v99, v104, v105
	v_cvt_pk_bf16_f32 v100, v100, v101
	v_cvt_pk_bf16_f32 v101, v106, v107
	v_lshl_add_u64 v[110:111], v[110:111], 0, s[100:101]
	global_store_dwordx4 v[110:111], v[98:101], off

.LBB0_238:
	s_andn2_b64 vcc, exec, s[24:25]
	s_cbranch_vccnz .LBB0_240
	v_mul_f32_e32 v98, v132, v106
	v_lshlrev_b64 v[100:101], 7, v[178:179]
	v_pk_mul_f32 v[94:95], v[94:95], v[98:99] op_sel_hi:[1,0]
	v_pk_mul_f32 v[96:97], v[96:97], v[98:99] op_sel_hi:[1,0]
	v_pk_mul_f32 v[102:103], v[92:93], v[98:99] op_sel_hi:[1,0]
	v_pk_mul_f32 v[92:93], v[90:91], v[98:99] op_sel_hi:[1,0]
	v_cvt_pk_bf16_f32 v90, v94, v95
	v_lshl_add_u64 v[94:95], s[98:99], 0, v[100:101]
	v_cvt_pk_bf16_f32 v91, v96, v97
	v_cvt_pk_bf16_f32 v92, v92, v93
	v_cvt_pk_bf16_f32 v93, v102, v103
	v_lshl_add_u64 v[94:95], v[130:131], 1, v[94:95]
	global_store_dwordx4 v[94:95], v[90:93], off
	v_pk_mul_f32 v[88:89], v[88:89], v[98:99] op_sel_hi:[1,0]
	v_pk_mul_f32 v[86:87], v[86:87], v[98:99] op_sel_hi:[1,0]
	v_pk_mul_f32 v[90:91], v[84:85], v[98:99] op_sel_hi:[1,0]
	v_pk_mul_f32 v[84:85], v[82:83], v[98:99] op_sel_hi:[1,0]
	v_cvt_pk_bf16_f32 v82, v86, v87
	v_cvt_pk_bf16_f32 v83, v88, v89
	v_cvt_pk_bf16_f32 v84, v84, v85
	v_cvt_pk_bf16_f32 v85, v90, v91
	v_lshl_add_u64 v[94:95], v[94:95], 0, s[100:101]
	global_store_dwordx4 v[94:95], v[82:85], off

.LBB0_244:
	s_andn2_b64 vcc, exec, s[24:25]
	s_cbranch_vccnz .LBB0_246
	v_mul_f32_e32 v82, v132, v90
	v_lshlrev_b64 v[84:85], 7, v[174:175]
	v_pk_mul_f32 v[78:79], v[78:79], v[82:83] op_sel_hi:[1,0]
	v_pk_mul_f32 v[80:81], v[80:81], v[82:83] op_sel_hi:[1,0]
	v_pk_mul_f32 v[86:87], v[76:77], v[82:83] op_sel_hi:[1,0]
	v_pk_mul_f32 v[76:77], v[74:75], v[82:83] op_sel_hi:[1,0]
	v_cvt_pk_bf16_f32 v74, v78, v79
	v_lshl_add_u64 v[78:79], s[98:99], 0, v[84:85]
	v_cvt_pk_bf16_f32 v75, v80, v81
	v_cvt_pk_bf16_f32 v76, v76, v77
	v_cvt_pk_bf16_f32 v77, v86, v87
	v_lshl_add_u64 v[78:79], v[130:131], 1, v[78:79]
	global_store_dwordx4 v[78:79], v[74:77], off
	v_pk_mul_f32 v[72:73], v[72:73], v[82:83] op_sel_hi:[1,0]
	v_pk_mul_f32 v[70:71], v[70:71], v[82:83] op_sel_hi:[1,0]
	v_pk_mul_f32 v[74:75], v[68:69], v[82:83] op_sel_hi:[1,0]
	v_pk_mul_f32 v[68:69], v[66:67], v[82:83] op_sel_hi:[1,0]
	v_cvt_pk_bf16_f32 v66, v70, v71
	v_cvt_pk_bf16_f32 v67, v72, v73
	v_cvt_pk_bf16_f32 v68, v68, v69
	v_cvt_pk_bf16_f32 v69, v74, v75
	v_lshl_add_u64 v[78:79], v[78:79], 0, s[100:101]
	global_store_dwordx4 v[78:79], v[66:69], off

.LBB0_250:
	s_andn2_b64 vcc, exec, s[24:25]
	s_cbranch_vccnz .LBB0_252
	v_mul_f32_e32 v66, v132, v74
	v_lshlrev_b64 v[68:69], 7, v[170:171]
	v_pk_mul_f32 v[62:63], v[62:63], v[66:67] op_sel_hi:[1,0]
	v_pk_mul_f32 v[64:65], v[64:65], v[66:67] op_sel_hi:[1,0]
	v_pk_mul_f32 v[70:71], v[60:61], v[66:67] op_sel_hi:[1,0]
	v_pk_mul_f32 v[60:61], v[58:59], v[66:67] op_sel_hi:[1,0]
	v_cvt_pk_bf16_f32 v58, v62, v63
	v_lshl_add_u64 v[62:63], s[98:99], 0, v[68:69]
	v_cvt_pk_bf16_f32 v59, v64, v65
	v_cvt_pk_bf16_f32 v60, v60, v61
	v_cvt_pk_bf16_f32 v61, v70, v71
	v_lshl_add_u64 v[62:63], v[130:131], 1, v[62:63]
	global_store_dwordx4 v[62:63], v[58:61], off
	v_pk_mul_f32 v[56:57], v[56:57], v[66:67] op_sel_hi:[1,0]
	v_pk_mul_f32 v[54:55], v[54:55], v[66:67] op_sel_hi:[1,0]
	v_pk_mul_f32 v[58:59], v[52:53], v[66:67] op_sel_hi:[1,0]
	v_pk_mul_f32 v[52:53], v[50:51], v[66:67] op_sel_hi:[1,0]
	v_cvt_pk_bf16_f32 v50, v54, v55
	v_cvt_pk_bf16_f32 v51, v56, v57
	v_cvt_pk_bf16_f32 v52, v52, v53
	v_cvt_pk_bf16_f32 v53, v58, v59
	v_lshl_add_u64 v[62:63], v[62:63], 0, s[100:101]
	global_store_dwordx4 v[62:63], v[50:53], off

.LBB0_256:
	s_andn2_b64 vcc, exec, s[24:25]
	s_cbranch_vccnz .LBB0_258
	v_mul_f32_e32 v50, v132, v58
	v_lshlrev_b64 v[52:53], 7, v[166:167]
	v_pk_mul_f32 v[46:47], v[46:47], v[50:51] op_sel_hi:[1,0]
	v_pk_mul_f32 v[48:49], v[48:49], v[50:51] op_sel_hi:[1,0]
	v_pk_mul_f32 v[54:55], v[44:45], v[50:51] op_sel_hi:[1,0]
	v_pk_mul_f32 v[44:45], v[42:43], v[50:51] op_sel_hi:[1,0]
	v_cvt_pk_bf16_f32 v42, v46, v47
	v_lshl_add_u64 v[46:47], s[98:99], 0, v[52:53]
	v_cvt_pk_bf16_f32 v43, v48, v49
	v_cvt_pk_bf16_f32 v44, v44, v45
	v_cvt_pk_bf16_f32 v45, v54, v55
	v_lshl_add_u64 v[46:47], v[130:131], 1, v[46:47]
	global_store_dwordx4 v[46:47], v[42:45], off
	v_pk_mul_f32 v[40:41], v[40:41], v[50:51] op_sel_hi:[1,0]
	v_pk_mul_f32 v[38:39], v[38:39], v[50:51] op_sel_hi:[1,0]
	v_pk_mul_f32 v[42:43], v[36:37], v[50:51] op_sel_hi:[1,0]
	v_pk_mul_f32 v[36:37], v[34:35], v[50:51] op_sel_hi:[1,0]
	v_cvt_pk_bf16_f32 v34, v38, v39
	v_cvt_pk_bf16_f32 v35, v40, v41
	v_cvt_pk_bf16_f32 v36, v36, v37
	v_cvt_pk_bf16_f32 v37, v42, v43
	v_lshl_add_u64 v[46:47], v[46:47], 0, s[100:101]
	global_store_dwordx4 v[46:47], v[34:37], off

.LBB0_262:
	s_andn2_b64 vcc, exec, s[24:25]
	s_cbranch_vccnz .LBB0_264
	v_mul_f32_e32 v34, v132, v42
	v_lshlrev_b64 v[36:37], 7, v[162:163]
	v_pk_mul_f32 v[30:31], v[30:31], v[34:35] op_sel_hi:[1,0]
	v_pk_mul_f32 v[32:33], v[32:33], v[34:35] op_sel_hi:[1,0]
	v_pk_mul_f32 v[38:39], v[28:29], v[34:35] op_sel_hi:[1,0]
	v_pk_mul_f32 v[28:29], v[26:27], v[34:35] op_sel_hi:[1,0]
	v_cvt_pk_bf16_f32 v26, v30, v31
	v_lshl_add_u64 v[30:31], s[98:99], 0, v[36:37]
	v_cvt_pk_bf16_f32 v27, v32, v33
	v_cvt_pk_bf16_f32 v28, v28, v29
	v_cvt_pk_bf16_f32 v29, v38, v39
	v_lshl_add_u64 v[30:31], v[130:131], 1, v[30:31]
	global_store_dwordx4 v[30:31], v[26:29], off
	v_pk_mul_f32 v[24:25], v[24:25], v[34:35] op_sel_hi:[1,0]
	v_pk_mul_f32 v[22:23], v[22:23], v[34:35] op_sel_hi:[1,0]
	v_pk_mul_f32 v[26:27], v[20:21], v[34:35] op_sel_hi:[1,0]
	v_pk_mul_f32 v[20:21], v[18:19], v[34:35] op_sel_hi:[1,0]
	v_cvt_pk_bf16_f32 v18, v22, v23
	v_cvt_pk_bf16_f32 v19, v24, v25
	v_cvt_pk_bf16_f32 v20, v20, v21
	v_cvt_pk_bf16_f32 v21, v26, v27
	v_lshl_add_u64 v[30:31], v[30:31], 0, s[100:101]
	global_store_dwordx4 v[30:31], v[18:21], off

.LBB0_270:
	v_mul_f32_e32 v18, v132, v26
	v_lshlrev_b64 v[20:21], 7, v[158:159]
	v_pk_mul_f32 v[14:15], v[14:15], v[18:19] op_sel_hi:[1,0]
	v_pk_mul_f32 v[16:17], v[16:17], v[18:19] op_sel_hi:[1,0]
	v_pk_mul_f32 v[22:23], v[12:13], v[18:19] op_sel_hi:[1,0]
	v_pk_mul_f32 v[12:13], v[10:11], v[18:19] op_sel_hi:[1,0]
	v_cvt_pk_bf16_f32 v10, v14, v15
	v_lshl_add_u64 v[14:15], s[98:99], 0, v[20:21]
	v_cvt_pk_bf16_f32 v11, v16, v17
	v_cvt_pk_bf16_f32 v12, v12, v13
	v_cvt_pk_bf16_f32 v13, v22, v23
	v_lshl_add_u64 v[14:15], v[130:131], 1, v[14:15]
	global_store_dwordx4 v[14:15], v[10:13], off
	v_pk_mul_f32 v[8:9], v[8:9], v[18:19] op_sel_hi:[1,0]
	v_pk_mul_f32 v[6:7], v[6:7], v[18:19] op_sel_hi:[1,0]
	v_pk_mul_f32 v[10:11], v[4:5], v[18:19] op_sel_hi:[1,0]
	v_pk_mul_f32 v[4:5], v[2:3], v[18:19] op_sel_hi:[1,0]
	v_cvt_pk_bf16_f32 v2, v6, v7
	v_cvt_pk_bf16_f32 v3, v8, v9
	v_cvt_pk_bf16_f32 v4, v4, v5
	v_cvt_pk_bf16_f32 v5, v10, v11
	v_lshl_add_u64 v[14:15], v[14:15], 0, s[100:101]
	global_store_dwordx4 v[14:15], v[2:5], off
	s_andn2_b64 vcc, exec, s[2:3]
	s_mov_b64 s[2:3], -1
	s_cbranch_vccnz .LBB0_211

	.amdhsa_kernel _Z8mega_fwd4Args
		.amdhsa_group_segment_fixed_size 0
		.amdhsa_private_segment_fixed_size 0
		.amdhsa_kernarg_size 376
		.amdhsa_user_sgpr_count 2
		.amdhsa_user_sgpr_dispatch_ptr 0
		.amdhsa_user_sgpr_queue_ptr 0
		.amdhsa_user_sgpr_kernarg_segment_ptr 1
		.amdhsa_user_sgpr_dispatch_id 0
		.amdhsa_user_sgpr_kernarg_preload_length 0
		.amdhsa_user_sgpr_kernarg_preload_offset 0
		.amdhsa_user_sgpr_private_segment_size 0
		.amdhsa_uses_dynamic_stack 0
		.amdhsa_enable_private_segment 0
		.amdhsa_system_sgpr_workgroup_id_x 1
		.amdhsa_system_sgpr_workgroup_id_y 0
		.amdhsa_system_sgpr_workgroup_id_z 0
		.amdhsa_system_sgpr_workgroup_info 0
		.amdhsa_system_vgpr_workitem_id 2
		.amdhsa_next_free_vgpr 256
		.amdhsa_next_free_sgpr 102
		.amdhsa_accum_offset 256
		.amdhsa_reserve_vcc 1
		.amdhsa_float_round_mode_32 0
		.amdhsa_float_round_mode_16_64 0
		.amdhsa_float_denorm_mode_32 3
		.amdhsa_float_denorm_mode_16_64 3
		.amdhsa_dx10_clamp 1
		.amdhsa_ieee_mode 1
		.amdhsa_fp16_overflow 0
		.amdhsa_tg_split 0
		.amdhsa_exception_fp_ieee_invalid_op 0
		.amdhsa_exception_fp_denorm_src 0
		.amdhsa_exception_fp_ieee_div_zero 0
		.amdhsa_exception_fp_ieee_overflow 0
		.amdhsa_exception_fp_ieee_underflow 0
		.amdhsa_exception_fp_ieee_inexact 0
		.amdhsa_exception_int_div_zero 0
	.end_amdhsa_kernel

amdhsa.kernels:
  - .agpr_count:     0
    .args:
      - .offset:         0
        .size:           120
        .value_kind:     by_value
      - .offset:         120
        .size:           4
        .value_kind:     hidden_block_count_x
      - .offset:         124
        .size:           4
        .value_kind:     hidden_block_count_y
      - .offset:         128
        .size:           4
        .value_kind:     hidden_block_count_z
      - .offset:         132
        .size:           2
        .value_kind:     hidden_group_size_x
      - .offset:         134
        .size:           2
        .value_kind:     hidden_group_size_y
      - .offset:         136
        .size:           2
        .value_kind:     hidden_group_size_z
      - .offset:         138
        .size:           2
        .value_kind:     hidden_remainder_x
      - .offset:         140
        .size:           2
        .value_kind:     hidden_remainder_y
      - .offset:         142
        .size:           2
        .value_kind:     hidden_remainder_z
      - .offset:         160
        .size:           8
        .value_kind:     hidden_global_offset_x
      - .offset:         168
        .size:           8
        .value_kind:     hidden_global_offset_y
      - .offset:         176
        .size:           8
        .value_kind:     hidden_global_offset_z
      - .offset:         184
        .size:           2
        .value_kind:     hidden_grid_dims
      - .offset:         208
        .size:           8
        .value_kind:     hidden_multigrid_sync_arg
      - .offset:         240
        .size:           4
        .value_kind:     hidden_dynamic_lds_size
    .group_segment_fixed_size: 0
    .kernarg_segment_align: 8
    .kernarg_segment_size: 376
    .language:       OpenCL C
    .language_version:
      - 2
      - 0
    .max_flat_workgroup_size: 512
    .name:           _Z8mega_fwd4Args
    .private_segment_fixed_size: 0
    .sgpr_count:     108
    .sgpr_spill_count: 95
    .symbol:         _Z8mega_fwd4Args.kd
    .uniform_work_group_size: 1
    .uses_dynamic_stack: false
    .vgpr_count:     256
    .vgpr_spill_count: 0
    .wavefront_size: 64
